# phase-12 SwiGLU epilogue: constant dequant scales folded into the exp argument and the sigmoid denominator (fma), removing 37 of 64 packed scale multiplies per wave
# speedup vs baseline: 1.0060x; 1.0060x over previous
; #define PG8_STAGE(bufoff, gbase, voff) do { _Pragma("unroll") for (int _i = 0; _i < 2; ++_i) \
;         __builtin_amdgcn_global_load_lds((const unsigned*)((const char*)(gbase) + (voff)[_i]), (LAS unsigned*)(lds + (bufoff) + ldsw + _i * 8192), 16, 0, 0); } while (0)
; #define PG8_WAIT_V(n) asm volatile("s_waitcnt vmcnt(" #n ")" ::: "memory")
; #define PG8_BAR __builtin_amdgcn_s_barrier()
;     const int wid = __builtin_amdgcn_readfirstlane(tid >> 6), lane = tid & 63, wr = wid >> 2, wc = wid & 3, fr = lane & 15, fq = lane >> 4;
;     const int K = g.K;
;     unsigned voffA[2], voffB[2];
; #pragma unroll
;     for (int i = 0; i < 2; ++i) { int R, C; stage_rc(tid * 16 + i * 8192, R, C); const int Rb = Epi::PERM ? ((R & ~31) + perm32(R & 31)) : R;
;         voffA[i] = (unsigned)(R * K + C) * 2u; voffB[i] = (unsigned)(Rb * K + C) * 2u; }
;     const size_t kstep = (size_t)(BK * 2);
;     const size_t hstep = (size_t)HALF * K * 2;
;     const size_t tstep = 2 * hstep;
;     const unsigned ldsw = (unsigned)wid * 1024u;
;     const int aoff = lds_byte(wr * 64 + fr, fq * 8), boff = lds_byte(wc * 32 + fr, fq * 8);
;     ...
;     Unit cur, nxt; int ui = 0;
;     if (!S.next(0, cur)) return;
;     const int sc1_ = 0x7F7F7F7F; (void)sc1_;
;     f32x4 acc[2][2][4][2];
; #pragma unroll
;     for (int a = 0; a < 2; ++a)
; #pragma unroll
;         for (int b = 0; b < 2; ++b)
; #pragma unroll
;             for (int m = 0; m < 4; ++m)
; #pragma unroll
;                 for (int n = 0; n < 2; ++n) acc[a][b][m][n] = (f32x4){0.f, 0.f, 0.f, 0.f};
;     bf16x8 At[4][2], B0[2][2], B1[2][2];
;     const char* cA = (const char*)g.A + (size_t)cur.pm * tstep + (size_t)cur.kt0 * kstep; const char* cB = (const char*)g.Bt + (size_t)cur.e * g.estride + (size_t)cur.pn * tstep + (size_t)cur.kt0 * kstep;
;     PG8_STAGE(PG8_SB(0, 0), cB, voffB); PG8_STAGE(PG8_SB(0, 1), cB + hstep, voffB); PG8_STAGE(PG8_SA(0, 0), cA, voffA); PG8_STAGE(PG8_SA(0, 1), cA + hstep, voffA);
;     if (wr == 1) PG8_BAR;
;     PG8_WAIT_V(2); PG8_BAR;
;     PG8_STAGE(PG8_SB(1, 0), cB + kstep, voffB); PG8_STAGE(PG8_SA(1, 0), cA + kstep, voffA); PG8_STAGE(PG8_SB(1, 1), cB + hstep + kstep, voffB);
;     PG8_WAIT_V(6); PG8_BAR;
.LBB0_4730:
	s_add_u32 s16, s56, 0x4b000000
	s_mov_b64 s[18:19], 0x80
	s_addc_u32 s17, s57, 0
	s_add_i32 m0, s43, 0x18000
	v_lshl_add_u64 v[8:9], v[8:9], 0, s[18:19]
	s_waitcnt vmcnt(2)
	s_barrier
	global_load_lds_dwordx4 v[8:9], off
	v_lshl_add_u64 v[6:7], v[6:7], 0, s[18:19]
	s_add_i32 m0, s43, 0x1a000
	s_add_i32 s58, s43, 0x8000
	global_load_lds_dwordx4 v[6:7], off
	v_lshl_add_u64 v[2:3], v[2:3], 0, s[18:19]
	s_mov_b32 m0, s58
	s_add_i32 s59, s43, 0xa000
	global_load_lds_dwordx4 v[2:3], off
	v_lshl_add_u64 v[2:3], v[4:5], 0, s[18:19]
	s_mov_b32 m0, s59
	s_mov_b64 s[20:21], 0x40080
	global_load_lds_dwordx4 v[2:3], off
	v_lshl_add_u64 v[2:3], v[0:1], 0, s[20:21]
	s_add_i32 m0, s43, 0x1c000
	v_lshl_add_u64 v[4:5], v[2:3], 0, v[128:129]
	global_load_lds_dwordx4 v[4:5], off
	v_lshl_add_u64 v[2:3], v[2:3], 0, v[134:135]
	s_add_i32 m0, s43, 0x1e000
	s_lshl_b32 s3, s3, 5
	global_load_lds_dwordx4 v[2:3], off
	v_lshrrev_b32_e32 v3, 1, v10
	v_and_b32_e32 v3, 24, v3
	v_and_b32_e32 v2, 15, v10
	v_lshlrev_b32_e32 v4, 1, v3
	v_lshl_or_b32 v148, s4, 6, v2
	v_lshl_or_b32 v2, v2, 6, v4
	v_lshlrev_b32_e32 v4, 2, v10
	s_lshl_b32 s4, s4, 13
	v_and_b32_e32 v4, 32, v4
	s_and_b32 s3, s3, 0x60
	v_bitop3_b32 v5, v2, s4, v4 bitop3:0xde
	s_lshl_b32 s4, s3, 7
	v_bitop3_b32 v149, s4, v2, v4 bitop3:0xf6
	v_lshlrev_b32_e32 v2, 14, v12
	v_and_b32_e32 v2, 0xffff8000, v2
	v_or_b32_e32 v150, s3, v3
	v_lshl_add_u32 v2, v13, 11, v2
	v_and_b32_e32 v3, 1, v12
	v_lshl_or_b32 v2, v3, 6, v2
	v_lshl_add_u32 v138, v15, 1, v2
	v_lshlrev_b32_e32 v2, 14, v11
	v_and_b32_e32 v2, 0xffff8000, v2
	s_waitcnt vmcnt(6)
	s_cmpk_lt_u32 s2, 0x100
	v_lshl_add_u32 v2, v14, 11, v2
	v_and_b32_e32 v3, 1, v11
	s_cselect_b64 s[24:25], -1, 0
	v_mov_b32_e32 v139, 0
	v_lshl_or_b32 v2, v3, 6, v2
	s_add_i32 s61, 0, 0x10000
	s_add_i32 s62, 0, 0x14000
	s_ashr_i32 s60, s33, 31
	v_ashrrev_i32_e32 v131, 31, v130
	v_lshl_add_u32 v140, v16, 1, v2
	v_mov_b32_e32 v141, v139
	s_mov_b64 s[26:27], 0x100
	v_add_u32_e32 v151, s61, v149
	v_add_u32_e32 v152, s62, v149
	v_add_u32_e32 v153, 0, v5
	s_mov_b32 s28, 0x3773ad84
	s_mov_b32 s30, 0x3973ad84
	s_mov_b32 s32, 0x4d8d45ca
	s_mov_b32 s63, 0xc3e00000
	s_movk_i32 s64, 0x1c00
	v_mov_b32_e32 v154, 0x43e00000
	global_load_dwordx4 v[230:233], v139, s[10:11]
	global_load_dwordx3 v[234:236], v139, s[10:11] offset:16
	s_waitcnt vmcnt(0)
	s_barrier
	s_branch .LBB0_4733

;     __device__ __forceinline__ float qscale(const Unit& u) const { return ((u.pn >= 8 && u.pn <= 11) || u.pn == 17) ? 0.5f : 1.0f; }
;     ...
;         if constexpr (QM == 2) { const float qs0_ = g.qs * E.qscale(cur), qs1_ = qs0_ * g.qs_b1; _Pragma("unroll") for (int a = 0; a < 2; ++a) _Pragma("unroll") for (int b = 0; b < 2; ++b) _Pragma("unroll") for (int m = 0; m < 4; ++m) _Pragma("unroll") for (int n = 0; n < 2; ++n) { const v4i t_ = __builtin_bit_cast(v4i, acc[a][b][m][n]); acc[a][b][m][n] = (f32x4){(float)t_[0], (float)t_[1], (float)t_[2], (float)t_[3]} * (b == 0 ? qs0_ : qs1_); } }
;     __device__ __forceinline__ void operator()(EPI_ARGS) const {
;     ...
;                 for (int n = 0; n < 2; ++n) { f32x4 g = acc[ai][0][m][n], up = acc[ai][1][m][n];
;                     if constexpr (!PRE) { g = g * ascale; up = up * ascale; }
;                     if constexpr (FOLD) { g = (g - cg[n] * mu) * rs + dg[n]; up = (up - cu[n] * mu) * rs + du[n]; }
;                     if constexpr (!PRE) up = up * oscale;
; #pragma unroll
;                     for (int j = 0; j < 4; ++j) { const float e = __builtin_amdgcn_exp2f(g[j] * -1.4426950408889634f); r[n][j] = g[j] * __builtin_amdgcn_rcpf(1.0f + e) * up[j]; } }
.LBB0_4741:
	v_cvt_f32_i32_e32 v147, v121
	v_cvt_f32_i32_e32 v146, v120
	v_cvt_f32_i32_e32 v145, v125
	v_cvt_f32_i32_e32 v144, v124
	v_cvt_f32_i32_e32 v120, v122
	v_cvt_f32_i32_e32 v121, v123
	v_mov_b32_e32 v122, v146
	v_mov_b32_e32 v123, v147
	v_cvt_f32_i32_e32 v147, v113
	v_cvt_f32_i32_e32 v146, v112
	v_cvt_f32_i32_e32 v125, v127
	v_cvt_f32_i32_e32 v124, v126
	v_mov_b32_e32 v126, v144
	v_mov_b32_e32 v127, v145
	v_cvt_f32_i32_e32 v145, v117
	v_cvt_f32_i32_e32 v144, v116
	v_cvt_f32_i32_e32 v112, v114
	v_cvt_f32_i32_e32 v113, v115
	v_mov_b32_e32 v114, v146
	v_mov_b32_e32 v115, v147
	v_cvt_f32_i32_e32 v147, v105
	v_cvt_f32_i32_e32 v146, v104
	v_cvt_f32_i32_e32 v117, v119
	v_cvt_f32_i32_e32 v116, v118
	v_mov_b32_e32 v118, v144
	v_mov_b32_e32 v119, v145
	v_cvt_f32_i32_e32 v145, v109
	v_cvt_f32_i32_e32 v144, v108
	v_cvt_f32_i32_e32 v104, v106
	v_cvt_f32_i32_e32 v105, v107
	v_mov_b32_e32 v106, v146
	v_mov_b32_e32 v107, v147
	v_cvt_f32_i32_e32 v147, v97
	v_cvt_f32_i32_e32 v146, v96
	v_cvt_f32_i32_e32 v109, v111
	v_cvt_f32_i32_e32 v108, v110
	v_mov_b32_e32 v110, v144
	v_mov_b32_e32 v111, v145
	v_cvt_f32_i32_e32 v145, v101
	v_cvt_f32_i32_e32 v144, v100
	v_cvt_f32_i32_e32 v96, v98
	v_cvt_f32_i32_e32 v97, v99
	v_mov_b32_e32 v98, v146
	v_mov_b32_e32 v99, v147
	v_cvt_f32_i32_e32 v146, v92
	v_cvt_f32_i32_e32 v147, v93
	v_cvt_f32_i32_e32 v92, v90
	v_cvt_f32_i32_e32 v93, v91
	v_cvt_f32_i32_e32 v90, v84
	v_cvt_f32_i32_e32 v91, v85
	v_cvt_f32_i32_e32 v84, v82
	v_cvt_f32_i32_e32 v85, v83
	v_cvt_f32_i32_e32 v82, v76
	v_cvt_f32_i32_e32 v83, v77
	v_cvt_f32_i32_e32 v76, v74
	v_cvt_f32_i32_e32 v77, v75
	v_cvt_f32_i32_e32 v75, v65
	v_cvt_f32_i32_e32 v74, v64
	v_cvt_f32_i32_e32 v101, v103
	v_cvt_f32_i32_e32 v100, v102
	v_mov_b32_e32 v102, v144
	v_mov_b32_e32 v103, v145
	v_cvt_f32_i32_e32 v144, v94
	v_cvt_f32_i32_e32 v145, v95
	v_cvt_f32_i32_e32 v94, v88
	v_cvt_f32_i32_e32 v95, v89
	v_cvt_f32_i32_e32 v88, v86
	v_cvt_f32_i32_e32 v89, v87
	v_cvt_f32_i32_e32 v86, v80
	v_cvt_f32_i32_e32 v87, v81
	v_cvt_f32_i32_e32 v80, v78
	v_cvt_f32_i32_e32 v81, v79
	v_cvt_f32_i32_e32 v78, v72
	v_cvt_f32_i32_e32 v79, v73
	v_cvt_f32_i32_e32 v73, v69
	v_cvt_f32_i32_e32 v72, v68
	v_cvt_f32_i32_e32 v64, v66
	v_cvt_f32_i32_e32 v65, v67
	v_mov_b32_e32 v66, v74
	v_mov_b32_e32 v67, v75
	v_cvt_f32_i32_e32 v75, v57
	v_cvt_f32_i32_e32 v74, v56
	v_cvt_f32_i32_e32 v69, v71
	v_cvt_f32_i32_e32 v68, v70
	v_mov_b32_e32 v70, v72
	v_mov_b32_e32 v71, v73
	v_cvt_f32_i32_e32 v73, v61
	v_cvt_f32_i32_e32 v72, v60
	v_cvt_f32_i32_e32 v56, v58
	v_cvt_f32_i32_e32 v57, v59
	v_mov_b32_e32 v58, v74
	v_mov_b32_e32 v59, v75
	v_cvt_f32_i32_e32 v75, v49
	v_cvt_f32_i32_e32 v74, v48
	v_cvt_f32_i32_e32 v61, v63
	v_cvt_f32_i32_e32 v60, v62
	v_mov_b32_e32 v62, v72
	v_mov_b32_e32 v63, v73
	v_cvt_f32_i32_e32 v73, v53
	v_cvt_f32_i32_e32 v72, v52
	v_cvt_f32_i32_e32 v48, v50
	v_cvt_f32_i32_e32 v49, v51
	v_mov_b32_e32 v50, v74
	v_mov_b32_e32 v51, v75
	v_cvt_f32_i32_e32 v75, v41
	v_cvt_f32_i32_e32 v74, v40
	v_cvt_f32_i32_e32 v53, v55
	v_cvt_f32_i32_e32 v52, v54
	v_mov_b32_e32 v54, v72
	v_mov_b32_e32 v55, v73
	v_cvt_f32_i32_e32 v73, v45
	v_cvt_f32_i32_e32 v72, v44
	v_cvt_f32_i32_e32 v40, v42
	v_cvt_f32_i32_e32 v41, v43
	v_mov_b32_e32 v42, v74
	v_mov_b32_e32 v43, v75
	v_cvt_f32_i32_e32 v75, v33
	v_cvt_f32_i32_e32 v74, v32
	v_cvt_f32_i32_e32 v45, v47
	v_cvt_f32_i32_e32 v44, v46
	v_mov_b32_e32 v46, v72
	v_mov_b32_e32 v47, v73
	v_cvt_f32_i32_e32 v73, v37
	v_cvt_f32_i32_e32 v72, v36
	v_cvt_f32_i32_e32 v32, v34
	v_cvt_f32_i32_e32 v33, v35
	v_mov_b32_e32 v34, v74
	v_mov_b32_e32 v35, v75
	v_cvt_f32_i32_e32 v74, v28
	v_cvt_f32_i32_e32 v75, v29
	v_cvt_f32_i32_e32 v28, v26
	v_cvt_f32_i32_e32 v29, v27
	v_cvt_f32_i32_e32 v26, v20
	v_cvt_f32_i32_e32 v27, v21
	v_cvt_f32_i32_e32 v20, v18
	v_cvt_f32_i32_e32 v21, v19
	v_cvt_f32_i32_e32 v18, v12
	v_cvt_f32_i32_e32 v19, v13
	v_cvt_f32_i32_e32 v12, v8
	v_cvt_f32_i32_e32 v13, v9
	v_cvt_f32_i32_e32 v8, v4
	v_cvt_f32_i32_e32 v9, v5
	v_cvt_f32_i32_e32 v4, v0
	v_cvt_f32_i32_e32 v5, v1
	v_mul_f32_e32 v0, 0xb7afc6c0, v126
	v_exp_f32_e32 v1, v0
	v_mul_f32_e32 v0, 0xb7afc6c0, v127
	v_cvt_f32_i32_e32 v37, v39
	v_cvt_f32_i32_e32 v36, v38
	v_mov_b32_e32 v38, v72
	v_mov_b32_e32 v39, v73
	v_cvt_f32_i32_e32 v72, v30
	v_cvt_f32_i32_e32 v73, v31
	v_cvt_f32_i32_e32 v30, v24
	v_cvt_f32_i32_e32 v31, v25
	v_cvt_f32_i32_e32 v24, v22
	v_cvt_f32_i32_e32 v25, v23
	v_cvt_f32_i32_e32 v22, v16
	v_cvt_f32_i32_e32 v23, v17
	v_cvt_f32_i32_e32 v16, v14
	v_cvt_f32_i32_e32 v17, v15
	v_exp_f32_e32 v14, v0
	v_fma_f32 v1, v1, s32, s32
	v_rcp_f32_e32 v15, v1
	v_fma_f32 v1, v14, s32, s32
	v_rcp_f32_e32 v14, v1
	v_mul_f32_e32 v15, v126, v15
	v_mul_f32_e32 v126, 0xb7afc6c0, v124
	v_exp_f32_e32 v126, v126
	v_mul_f32_e32 v14, v127, v14
	v_mul_f32_e32 v127, 0xb7afc6c0, v125
	v_exp_f32_e32 v127, v127
	v_mul_f32_e32 v15, v146, v15
	v_fma_f32 v126, v126, s32, s32
	v_mul_f32_e32 v146, 0xb7afc6c0, v122
	v_rcp_f32_e32 v126, v126
	v_fma_f32 v127, v127, s32, s32
	v_exp_f32_e32 v146, v146
	v_rcp_f32_e32 v127, v127
	v_mul_f32_e32 v124, v124, v126
	v_mul_f32_e32 v14, v147, v14
	v_fma_f32 v126, v146, s32, s32
	v_mul_f32_e32 v125, v125, v127
	v_rcp_f32_e32 v126, v126
	v_mul_f32_e32 v127, 0xb7afc6c0, v123
	v_exp_f32_e32 v127, v127
	v_med3_f32 v15, v15, s63, v154
	v_mul_f32_e32 v122, v122, v126
	v_mul_f32_e32 v94, v94, v122
	v_fma_f32 v122, v127, s32, s32
	v_mul_f32_e32 v126, 0xb7afc6c0, v120
	v_rcp_f32_e32 v122, v122
	v_exp_f32_e32 v126, v126
	v_mul_f32_e32 v127, 0xb7afc6c0, v121
	v_exp_f32_e32 v127, v127
	v_mul_f32_e32 v122, v123, v122
	v_fma_f32 v123, v126, s32, s32
	v_rcp_f32_e32 v123, v123
	v_fma_f32 v126, v127, s32, s32
	v_rcp_f32_e32 v126, v126
; __device__ __forceinline__ u32x4 pack8bf(const f32x4 a, const f32x4 b) { u32x4 w; w.x = cvt_pk_bf16(a[0], a[1]); w.y = cvt_pk_bf16(a[2], a[3]); w.z = cvt_pk_bf16(b[0], b[1]); w.w = cvt_pk_bf16(b[2], b[3]); return w; }
;     __device__ __forceinline__ void operator()(EPI_ARGS) const {
;     ...
;                 for (int n = 0; n < 2; ++n) { f32x4 g = acc[ai][0][m][n], up = acc[ai][1][m][n];
;                     if constexpr (!PRE) { g = g * ascale; up = up * ascale; }
;                     if constexpr (FOLD) { g = (g - cg[n] * mu) * rs + dg[n]; up = (up - cu[n] * mu) * rs + du[n]; }
;                     if constexpr (!PRE) up = up * oscale;
; #pragma unroll
;                     for (int j = 0; j < 4; ++j) { const float e = __builtin_amdgcn_exp2f(g[j] * -1.4426950408889634f); r[n][j] = g[j] * __builtin_amdgcn_rcpf(1.0f + e) * up[j]; } }
;                 if constexpr (F8OUT) *(u32x2*)((unsigned char*)O + (size_t)row * ldc + col0) = pack8fp8(r[0], r[1]);
;                 else *(u32x4*)((bf16_t*)O + (size_t)row * ldc + col0) = pack8bf(r[0], r[1]); }
	v_med3_f32 v14, v14, s63, v154
	v_mul_f32_e32 v120, v120, v123
	v_mul_f32_e32 v120, v92, v120
	v_mul_f32_e32 v92, v121, v126
	v_mul_f32_e32 v121, v93, v92
	v_cvt_pk_fp8_f32 v92, v15, v14
	v_mul_f32_e32 v95, v95, v122
	v_mul_f32_e32 v124, v144, v124
	v_mul_f32_e32 v125, v145, v125
	v_med3_f32 v94, v94, s63, v154
	v_med3_f32 v95, v95, s63, v154
	v_med3_f32 v14, v124, s63, v154
	v_med3_f32 v15, v125, s63, v154
	v_cvt_pk_fp8_f32 v93, v94, v95
	v_cvt_pk_fp8_f32 v92, v14, v15 op_sel:[0,0,1]
	v_med3_f32 v14, v120, s63, v154
	v_mul_f32_e32 v120, 0xb7afc6c0, v118
	v_med3_f32 v15, v121, s63, v154
	v_exp_f32_e32 v120, v120
	v_mul_f32_e32 v121, 0xb7afc6c0, v119
	v_exp_f32_e32 v121, v121
	v_cvt_pk_fp8_f32 v93, v14, v15 op_sel:[0,0,1]
	v_lshl_add_u32 v156, s44, 8, v148
	v_lshl_or_b32 v0, s42, 7, v150
	v_mov_b64_e32 v[14:15], s[16:17]
	v_ashrrev_i32_e32 v1, 31, v0
	v_mad_i64_i32 v[94:95], s[4:5], v156, s64, v[14:15]
	v_fma_f32 v120, v120, s32, s32
	v_lshl_add_u64 v[94:95], v[94:95], 0, v[0:1]
	v_rcp_f32_e32 v120, v120
	v_fma_f32 v121, v121, s32, s32
	v_rcp_f32_e32 v121, v121
	global_store_dwordx2 v[94:95], v[92:93], off
	v_mul_f32_e32 v93, 0xb7afc6c0, v116
	v_exp_f32_e32 v93, v93
	v_mul_f32_e32 v94, 0xb7afc6c0, v117
	v_exp_f32_e32 v94, v94
	v_mul_f32_e32 v92, v118, v120
	v_mul_f32_e32 v90, v90, v92
	v_mul_f32_e32 v92, v119, v121
	v_mul_f32_e32 v91, v91, v92
	v_fma_f32 v92, v93, s32, s32
	v_rcp_f32_e32 v92, v92
	v_fma_f32 v93, v94, s32, s32
	v_mul_f32_e32 v94, 0xb7afc6c0, v114
	v_rcp_f32_e32 v93, v93
	v_exp_f32_e32 v94, v94
	v_mul_f32_e32 v92, v116, v92
	v_mul_f32_e32 v88, v88, v92
	v_mul_f32_e32 v92, v117, v93
	v_fma_f32 v93, v94, s32, s32
	v_rcp_f32_e32 v93, v93
	v_mul_f32_e32 v94, 0xb7afc6c0, v115
	v_exp_f32_e32 v94, v94
	v_mul_f32_e32 v89, v89, v92
	v_mul_f32_e32 v92, v114, v93
	v_mul_f32_e32 v93, 0xb7afc6c0, v112
	v_mul_f32_e32 v86, v86, v92
	v_fma_f32 v92, v94, s32, s32
	v_exp_f32_e32 v93, v93
	v_mul_f32_e32 v94, 0xb7afc6c0, v113
	v_exp_f32_e32 v94, v94
	v_rcp_f32_e32 v92, v92
	v_fma_f32 v93, v93, s32, s32
	v_rcp_f32_e32 v93, v93
	v_fma_f32 v94, v94, s32, s32
	v_rcp_f32_e32 v94, v94
	v_mul_f32_e32 v92, v115, v92
	v_mul_f32_e32 v87, v87, v92
	v_mul_f32_e32 v92, v112, v93
	v_mul_f32_e32 v92, v84, v92
	v_mul_f32_e32 v84, v113, v94
	v_mul_f32_e32 v93, v85, v84
	v_med3_f32 v85, v90, s63, v154
	v_med3_f32 v90, v91, s63, v154
	v_cvt_pk_fp8_f32 v84, v85, v90
	v_med3_f32 v86, v86, s63, v154
	v_med3_f32 v87, v87, s63, v154
	v_med3_f32 v88, v88, s63, v154
	v_med3_f32 v89, v89, s63, v154
	v_cvt_pk_fp8_f32 v85, v86, v87
	v_cvt_pk_fp8_f32 v84, v88, v89 op_sel:[0,0,1]
	v_mul_f32_e32 v88, 0xb7afc6c0, v110
	v_exp_f32_e32 v88, v88
	v_mul_f32_e32 v89, 0xb7afc6c0, v111
	v_med3_f32 v86, v92, s63, v154
	v_med3_f32 v87, v93, s63, v154
	v_exp_f32_e32 v89, v89
	v_cvt_pk_fp8_f32 v85, v86, v87 op_sel:[0,0,1]
	v_or_b32_e32 v94, 16, v156
	v_mad_i64_i32 v[86:87], s[4:5], v94, s64, v[14:15]
	v_fma_f32 v88, v88, s32, s32
	v_lshl_add_u64 v[86:87], v[86:87], 0, v[0:1]
	v_rcp_f32_e32 v88, v88
	v_fma_f32 v89, v89, s32, s32
	v_rcp_f32_e32 v89, v89
	global_store_dwordx2 v[86:87], v[84:85], off
	v_mul_f32_e32 v85, 0xb7afc6c0, v108
	v_exp_f32_e32 v85, v85
	v_mul_f32_e32 v86, 0xb7afc6c0, v109
	v_exp_f32_e32 v86, v86
	v_mul_f32_e32 v84, v110, v88
	v_mul_f32_e32 v82, v82, v84
	v_mul_f32_e32 v84, v111, v89
	v_mul_f32_e32 v83, v83, v84
	v_fma_f32 v84, v85, s32, s32
	v_rcp_f32_e32 v84, v84
	v_fma_f32 v85, v86, s32, s32
	v_mul_f32_e32 v86, 0xb7afc6c0, v106
	v_rcp_f32_e32 v85, v85
	v_exp_f32_e32 v86, v86
	v_mul_f32_e32 v84, v108, v84
	v_mul_f32_e32 v80, v80, v84
	v_mul_f32_e32 v84, v109, v85
	v_fma_f32 v85, v86, s32, s32
	v_rcp_f32_e32 v85, v85
	v_mul_f32_e32 v86, 0xb7afc6c0, v107
	v_exp_f32_e32 v86, v86
	v_mul_f32_e32 v81, v81, v84
	v_mul_f32_e32 v84, v106, v85
	v_mul_f32_e32 v85, 0xb7afc6c0, v104
	v_mul_f32_e32 v78, v78, v84
	v_fma_f32 v84, v86, s32, s32
	v_exp_f32_e32 v85, v85
	v_mul_f32_e32 v86, 0xb7afc6c0, v105
	v_exp_f32_e32 v86, v86
	v_rcp_f32_e32 v84, v84
	v_fma_f32 v85, v85, s32, s32
	v_rcp_f32_e32 v85, v85
	v_fma_f32 v86, v86, s32, s32
	v_rcp_f32_e32 v86, v86
	v_mul_f32_e32 v84, v107, v84
	v_mul_f32_e32 v79, v79, v84
	v_mul_f32_e32 v84, v104, v85
	v_mul_f32_e32 v84, v76, v84
	v_mul_f32_e32 v76, v105, v86
	v_mul_f32_e32 v85, v77, v76
	v_med3_f32 v77, v82, s63, v154
	v_med3_f32 v82, v83, s63, v154
	v_cvt_pk_fp8_f32 v76, v77, v82
	v_med3_f32 v78, v78, s63, v154
	v_med3_f32 v79, v79, s63, v154
	v_med3_f32 v80, v80, s63, v154
	v_med3_f32 v81, v81, s63, v154
	v_cvt_pk_fp8_f32 v77, v78, v79
	v_cvt_pk_fp8_f32 v76, v80, v81 op_sel:[0,0,1]
	v_mul_f32_e32 v80, 0xb7afc6c0, v102
	v_exp_f32_e32 v80, v80
	v_mul_f32_e32 v81, 0xb7afc6c0, v103
	v_med3_f32 v78, v84, s63, v154
	v_med3_f32 v79, v85, s63, v154
	v_exp_f32_e32 v81, v81
	v_cvt_pk_fp8_f32 v77, v78, v79 op_sel:[0,0,1]
	v_or_b32_e32 v86, 32, v156
	v_mad_i64_i32 v[78:79], s[4:5], v86, s64, v[14:15]
	v_fma_f32 v80, v80, s32, s32
	v_lshl_add_u64 v[78:79], v[78:79], 0, v[0:1]
	v_rcp_f32_e32 v80, v80
	v_fma_f32 v81, v81, s32, s32
	v_rcp_f32_e32 v81, v81
	global_store_dwordx2 v[78:79], v[76:77], off
	v_mul_f32_e32 v77, 0xb7afc6c0, v100
	v_exp_f32_e32 v77, v77
	v_mul_f32_e32 v78, 0xb7afc6c0, v101
	v_exp_f32_e32 v78, v78
	v_mul_f32_e32 v76, v102, v80
	v_mul_f32_e32 v70, v70, v76
	v_mul_f32_e32 v76, v103, v81
	v_mul_f32_e32 v71, v71, v76
	v_fma_f32 v76, v77, s32, s32
	v_rcp_f32_e32 v76, v76
	v_fma_f32 v77, v78, s32, s32
	v_mul_f32_e32 v78, 0xb7afc6c0, v98
	v_rcp_f32_e32 v77, v77
	v_exp_f32_e32 v78, v78
	v_mul_f32_e32 v76, v100, v76
	v_mul_f32_e32 v68, v68, v76
	v_mul_f32_e32 v76, v101, v77
	v_fma_f32 v77, v78, s32, s32
	v_rcp_f32_e32 v77, v77
; __device__ __forceinline__ u32x4 pack8bf(const f32x4 a, const f32x4 b) { u32x4 w; w.x = cvt_pk_bf16(a[0], a[1]); w.y = cvt_pk_bf16(a[2], a[3]); w.z = cvt_pk_bf16(b[0], b[1]); w.w = cvt_pk_bf16(b[2], b[3]); return w; }
;     __device__ __forceinline__ void operator()(EPI_ARGS) const {
;     ...
;                 for (int n = 0; n < 2; ++n) { f32x4 g = acc[ai][0][m][n], up = acc[ai][1][m][n];
;                     if constexpr (!PRE) { g = g * ascale; up = up * ascale; }
;                     if constexpr (FOLD) { g = (g - cg[n] * mu) * rs + dg[n]; up = (up - cu[n] * mu) * rs + du[n]; }
;                     if constexpr (!PRE) up = up * oscale;
; #pragma unroll
;                     for (int j = 0; j < 4; ++j) { const float e = __builtin_amdgcn_exp2f(g[j] * -1.4426950408889634f); r[n][j] = g[j] * __builtin_amdgcn_rcpf(1.0f + e) * up[j]; } }
;                 if constexpr (F8OUT) *(u32x2*)((unsigned char*)O + (size_t)row * ldc + col0) = pack8fp8(r[0], r[1]);
;                 else *(u32x4*)((bf16_t*)O + (size_t)row * ldc + col0) = pack8bf(r[0], r[1]); }
	v_mul_f32_e32 v78, 0xb7afc6c0, v99
	v_exp_f32_e32 v78, v78
	v_mul_f32_e32 v69, v69, v76
	v_mul_f32_e32 v76, v98, v77
	v_mul_f32_e32 v77, 0xb7afc6c0, v96
	v_mul_f32_e32 v66, v66, v76
	v_fma_f32 v76, v78, s32, s32
	v_exp_f32_e32 v77, v77
	v_mul_f32_e32 v78, 0xb7afc6c0, v97
	v_exp_f32_e32 v78, v78
	v_rcp_f32_e32 v76, v76
	v_fma_f32 v77, v77, s32, s32
	v_rcp_f32_e32 v77, v77
	v_fma_f32 v78, v78, s32, s32
	v_rcp_f32_e32 v78, v78
	v_mul_f32_e32 v76, v99, v76
	v_mul_f32_e32 v67, v67, v76
	v_mul_f32_e32 v76, v96, v77
	v_mul_f32_e32 v76, v64, v76
	v_mul_f32_e32 v64, v97, v78
	v_mul_f32_e32 v77, v65, v64
	v_med3_f32 v65, v70, s63, v154
	v_med3_f32 v70, v71, s63, v154
	v_cvt_pk_fp8_f32 v64, v65, v70
	v_med3_f32 v66, v66, s63, v154
	v_med3_f32 v67, v67, s63, v154
	v_cvt_pk_fp8_f32 v65, v66, v67
	v_med3_f32 v68, v68, s63, v154
	v_med3_f32 v69, v69, s63, v154
	v_cvt_pk_fp8_f32 v64, v68, v69 op_sel:[0,0,1]
	v_med3_f32 v66, v76, s63, v154
	v_med3_f32 v67, v77, s63, v154
	v_mul_f32_e32 v68, 0xb7afc6c0, v62
	v_cvt_pk_fp8_f32 v65, v66, v67 op_sel:[0,0,1]
	v_exp_f32_e32 v68, v68
	v_mul_f32_e32 v69, 0xb7afc6c0, v63
	v_or_b32_e32 v78, 48, v156
	v_exp_f32_e32 v69, v69
	v_mad_i64_i32 v[66:67], s[4:5], v78, s64, v[14:15]
	v_lshl_add_u64 v[66:67], v[66:67], 0, v[0:1]
	global_store_dwordx2 v[66:67], v[64:65], off
	v_fma_f32 v64, v68, s32, s32
	v_rcp_f32_e32 v64, v64
	v_fma_f32 v65, v69, s32, s32
	v_rcp_f32_e32 v65, v65
	v_mul_f32_e32 v62, v62, v64
	v_mul_f32_e32 v64, 0xb7afc6c0, v60
	v_mul_f32_e32 v63, v63, v65
	v_exp_f32_e32 v64, v64
	v_mul_f32_e32 v65, 0xb7afc6c0, v61
	v_exp_f32_e32 v65, v65
	v_mul_f32_e32 v67, 0xb7afc6c0, v58
	v_fma_f32 v64, v64, s32, s32
	v_rcp_f32_e32 v64, v64
	v_fma_f32 v65, v65, s32, s32
	v_exp_f32_e32 v67, v67
	v_rcp_f32_e32 v65, v65
	v_mul_f32_e32 v60, v60, v64
	v_mul_f32_e32 v62, v74, v62
	v_fma_f32 v64, v67, s32, s32
	v_mul_f32_e32 v61, v61, v65
	v_rcp_f32_e32 v64, v64
	v_mul_f32_e32 v65, 0xb7afc6c0, v59
	v_exp_f32_e32 v65, v65
	v_mul_f32_e32 v63, v75, v63
	v_mul_f32_e32 v58, v58, v64
	v_mul_f32_e32 v30, v30, v58
	v_fma_f32 v58, v65, s32, s32
	v_mul_f32_e32 v64, 0xb7afc6c0, v56
	v_rcp_f32_e32 v58, v58
	v_exp_f32_e32 v64, v64
	v_mul_f32_e32 v65, 0xb7afc6c0, v57
	v_exp_f32_e32 v65, v65
	v_mul_f32_e32 v58, v59, v58
	v_fma_f32 v59, v64, s32, s32
	v_rcp_f32_e32 v59, v59
	v_fma_f32 v64, v65, s32, s32
	v_rcp_f32_e32 v64, v64
	v_mul_f32_e32 v31, v31, v58
	v_mul_f32_e32 v56, v56, v59
	v_mul_f32_e32 v56, v28, v56
	v_mul_f32_e32 v28, v57, v64
	v_mul_f32_e32 v57, v29, v28
	v_med3_f32 v29, v62, s63, v154
	v_med3_f32 v58, v63, s63, v154
	v_cvt_pk_fp8_f32 v28, v29, v58
	v_med3_f32 v30, v30, s63, v154
	v_med3_f32 v31, v31, s63, v154
	v_cvt_pk_fp8_f32 v29, v30, v31
	v_med3_f32 v30, v56, s63, v154
	v_mul_f32_e32 v56, 0xb7afc6c0, v54
	v_mul_f32_e32 v60, v72, v60
	v_mul_f32_e32 v61, v73, v61
	v_med3_f32 v31, v57, s63, v154
	v_exp_f32_e32 v56, v56
	v_mul_f32_e32 v57, 0xb7afc6c0, v55
	v_med3_f32 v58, v60, s63, v154
	v_med3_f32 v59, v61, s63, v154
	v_exp_f32_e32 v57, v57
	v_cvt_pk_fp8_f32 v28, v58, v59 op_sel:[0,0,1]
	v_cvt_pk_fp8_f32 v29, v30, v31 op_sel:[0,0,1]
	v_add_u32_e32 v66, 0x80, v156
	v_mad_i64_i32 v[30:31], s[4:5], v66, s64, v[14:15]
	v_fma_f32 v56, v56, s32, s32
	v_lshl_add_u64 v[30:31], v[30:31], 0, v[0:1]
	v_rcp_f32_e32 v56, v56
	v_fma_f32 v57, v57, s32, s32
	v_rcp_f32_e32 v57, v57
	global_store_dwordx2 v[30:31], v[28:29], off
	v_mul_f32_e32 v29, 0xb7afc6c0, v52
	v_exp_f32_e32 v29, v29
	v_mul_f32_e32 v30, 0xb7afc6c0, v53
	v_exp_f32_e32 v30, v30
	v_mul_f32_e32 v28, v54, v56
	v_mul_f32_e32 v26, v26, v28
	v_mul_f32_e32 v28, v55, v57
	v_mul_f32_e32 v27, v27, v28
	v_fma_f32 v28, v29, s32, s32
	v_rcp_f32_e32 v28, v28
	v_fma_f32 v29, v30, s32, s32
	v_mul_f32_e32 v30, 0xb7afc6c0, v50
	v_rcp_f32_e32 v29, v29
	v_exp_f32_e32 v30, v30
	v_mul_f32_e32 v28, v52, v28
	v_mul_f32_e32 v24, v24, v28
	v_mul_f32_e32 v28, v53, v29
	v_fma_f32 v29, v30, s32, s32
	v_rcp_f32_e32 v29, v29
	v_mul_f32_e32 v30, 0xb7afc6c0, v51
	v_exp_f32_e32 v30, v30
	v_mul_f32_e32 v25, v25, v28
	v_mul_f32_e32 v28, v50, v29
	v_mul_f32_e32 v29, 0xb7afc6c0, v48
	v_mul_f32_e32 v22, v22, v28
	v_fma_f32 v28, v30, s32, s32
	v_exp_f32_e32 v29, v29
	v_mul_f32_e32 v30, 0xb7afc6c0, v49
	v_exp_f32_e32 v30, v30
	v_rcp_f32_e32 v28, v28
	v_fma_f32 v29, v29, s32, s32
	v_rcp_f32_e32 v29, v29
	v_fma_f32 v30, v30, s32, s32
	v_rcp_f32_e32 v30, v30
	v_mul_f32_e32 v28, v51, v28
	v_mul_f32_e32 v23, v23, v28
	v_mul_f32_e32 v28, v48, v29
	v_mul_f32_e32 v28, v20, v28
	v_mul_f32_e32 v20, v49, v30
	v_mul_f32_e32 v29, v21, v20
	v_med3_f32 v21, v26, s63, v154
	v_med3_f32 v26, v27, s63, v154
	v_cvt_pk_fp8_f32 v20, v21, v26
	v_med3_f32 v22, v22, s63, v154
; __device__ __forceinline__ u32x4 pack8bf(const f32x4 a, const f32x4 b) { u32x4 w; w.x = cvt_pk_bf16(a[0], a[1]); w.y = cvt_pk_bf16(a[2], a[3]); w.z = cvt_pk_bf16(b[0], b[1]); w.w = cvt_pk_bf16(b[2], b[3]); return w; }
;     __device__ __forceinline__ float qscale(const Unit& u) const { return ((u.pn >= 8 && u.pn <= 11) || u.pn == 17) ? 0.5f : 1.0f; }
; __device__ __forceinline__ void ln_stats(const float* st, int row, float& mu, float& rs) { const f32x2 s = *(const f32x2*)(st + 2 * (size_t)row); mu = s[0] * (1.0f / DM); rs = 1.0f / sqrtf(s[1] * (1.0f / DM) - mu * mu + LN_EPS); }
;     ...
;         if constexpr (QM == 2) { const float qs0_ = g.qs * E.qscale(cur), qs1_ = qs0_ * g.qs_b1; _Pragma("unroll") for (int a = 0; a < 2; ++a) _Pragma("unroll") for (int b = 0; b < 2; ++b) _Pragma("unroll") for (int m = 0; m < 4; ++m) _Pragma("unroll") for (int n = 0; n < 2; ++n) { const v4i t_ = __builtin_bit_cast(v4i, acc[a][b][m][n]); acc[a][b][m][n] = (f32x4){(float)t_[0], (float)t_[1], (float)t_[2], (float)t_[3]} * (b == 0 ? qs0_ : qs1_); } }
;     __device__ __forceinline__ void operator()(EPI_ARGS) const {
;     ...
; #pragma unroll
;         for (int ai = 0; ai < 2; ++ai)
; #pragma unroll
;             for (int m = 0; m < 4; ++m) { const int row = row0 + ai * HALF + m * 16; f32x4 r[2];
;                 float mu = 0.f, rs = 1.f; if constexpr (FOLD) ln_stats(st, row, mu, rs);
; #pragma unroll
;                 for (int n = 0; n < 2; ++n) { f32x4 g = acc[ai][0][m][n], up = acc[ai][1][m][n];
;                     if constexpr (!PRE) { g = g * ascale; up = up * ascale; }
;                     if constexpr (FOLD) { g = (g - cg[n] * mu) * rs + dg[n]; up = (up - cu[n] * mu) * rs + du[n]; }
;                     if constexpr (!PRE) up = up * oscale;
; #pragma unroll
;                     for (int j = 0; j < 4; ++j) { const float e = __builtin_amdgcn_exp2f(g[j] * -1.4426950408889634f); r[n][j] = g[j] * __builtin_amdgcn_rcpf(1.0f + e) * up[j]; } }
;                 if constexpr (F8OUT) *(u32x2*)((unsigned char*)O + (size_t)row * ldc + col0) = pack8fp8(r[0], r[1]);
;                 else *(u32x4*)((bf16_t*)O + (size_t)row * ldc + col0) = pack8bf(r[0], r[1]); }
	v_med3_f32 v23, v23, s63, v154
	v_med3_f32 v24, v24, s63, v154
	v_med3_f32 v25, v25, s63, v154
	v_cvt_pk_fp8_f32 v21, v22, v23
	v_cvt_pk_fp8_f32 v20, v24, v25 op_sel:[0,0,1]
	v_mul_f32_e32 v24, 0xb7afc6c0, v46
	v_exp_f32_e32 v24, v24
	v_mul_f32_e32 v25, 0xb7afc6c0, v47
	v_med3_f32 v22, v28, s63, v154
	v_med3_f32 v23, v29, s63, v154
	v_exp_f32_e32 v25, v25
	v_cvt_pk_fp8_f32 v21, v22, v23 op_sel:[0,0,1]
	v_add_u32_e32 v30, 0x90, v156
	v_mad_i64_i32 v[22:23], s[4:5], v30, s64, v[14:15]
	v_fma_f32 v24, v24, s32, s32
	v_lshl_add_u64 v[22:23], v[22:23], 0, v[0:1]
	v_rcp_f32_e32 v24, v24
	v_fma_f32 v25, v25, s32, s32
	v_rcp_f32_e32 v25, v25
	global_store_dwordx2 v[22:23], v[20:21], off
	v_mul_f32_e32 v21, 0xb7afc6c0, v44
	v_exp_f32_e32 v21, v21
	v_mul_f32_e32 v22, 0xb7afc6c0, v45
	v_exp_f32_e32 v22, v22
	v_mul_f32_e32 v20, v46, v24
	v_mul_f32_e32 v18, v18, v20
	v_mul_f32_e32 v20, v47, v25
	v_mul_f32_e32 v19, v19, v20
	v_fma_f32 v20, v21, s32, s32
	v_rcp_f32_e32 v20, v20
	v_fma_f32 v21, v22, s32, s32
	v_mul_f32_e32 v22, 0xb7afc6c0, v42
	v_rcp_f32_e32 v21, v21
	v_exp_f32_e32 v22, v22
	v_mul_f32_e32 v20, v44, v20
	v_mul_f32_e32 v16, v16, v20
	v_mul_f32_e32 v20, v45, v21
	v_fma_f32 v21, v22, s32, s32
	v_rcp_f32_e32 v21, v21
	v_mul_f32_e32 v22, 0xb7afc6c0, v43
	v_exp_f32_e32 v22, v22
	v_mul_f32_e32 v17, v17, v20
	v_mul_f32_e32 v20, v42, v21
	v_mul_f32_e32 v21, 0xb7afc6c0, v40
	v_mul_f32_e32 v12, v12, v20
	v_fma_f32 v20, v22, s32, s32
	v_exp_f32_e32 v21, v21
	v_mul_f32_e32 v22, 0xb7afc6c0, v41
	v_exp_f32_e32 v22, v22
	v_rcp_f32_e32 v20, v20
	v_fma_f32 v21, v21, s32, s32
	v_rcp_f32_e32 v21, v21
	v_fma_f32 v22, v22, s32, s32
	v_rcp_f32_e32 v22, v22
	v_mul_f32_e32 v20, v43, v20
	v_cvt_f32_i32_e32 v10, v10
	v_cvt_f32_i32_e32 v11, v11
	v_mul_f32_e32 v13, v13, v20
	v_mul_f32_e32 v20, v40, v21
	v_mul_f32_e32 v20, v10, v20
	v_mul_f32_e32 v10, v41, v22
	v_mul_f32_e32 v21, v11, v10
	v_med3_f32 v11, v18, s63, v154
	v_med3_f32 v18, v19, s63, v154
	v_cvt_pk_fp8_f32 v10, v11, v18
	v_med3_f32 v12, v12, s63, v154
	v_med3_f32 v13, v13, s63, v154
	v_med3_f32 v16, v16, s63, v154
	v_med3_f32 v17, v17, s63, v154
	v_cvt_pk_fp8_f32 v11, v12, v13
	v_cvt_pk_fp8_f32 v10, v16, v17 op_sel:[0,0,1]
	v_mul_f32_e32 v16, 0xb7afc6c0, v38
	v_exp_f32_e32 v16, v16
	v_mul_f32_e32 v17, 0xb7afc6c0, v39
	v_med3_f32 v12, v20, s63, v154
	v_med3_f32 v13, v21, s63, v154
	v_exp_f32_e32 v17, v17
	v_cvt_pk_fp8_f32 v11, v12, v13 op_sel:[0,0,1]
	v_add_u32_e32 v22, 0xa0, v156
	v_mad_i64_i32 v[12:13], s[4:5], v22, s64, v[14:15]
	v_fma_f32 v16, v16, s32, s32
	v_lshl_add_u64 v[12:13], v[12:13], 0, v[0:1]
	v_rcp_f32_e32 v16, v16
	v_fma_f32 v17, v17, s32, s32
	v_rcp_f32_e32 v17, v17
	global_store_dwordx2 v[12:13], v[10:11], off
	v_mul_f32_e32 v11, 0xb7afc6c0, v36
	v_exp_f32_e32 v11, v11
	v_mul_f32_e32 v12, 0xb7afc6c0, v37
	v_exp_f32_e32 v12, v12
	v_mul_f32_e32 v10, v38, v16
	v_mul_f32_e32 v8, v8, v10
	v_mul_f32_e32 v10, v39, v17
	v_mul_f32_e32 v9, v9, v10
	v_fma_f32 v10, v11, s32, s32
	v_rcp_f32_e32 v10, v10
	v_fma_f32 v11, v12, s32, s32
	v_mul_f32_e32 v12, 0xb7afc6c0, v34
	v_rcp_f32_e32 v11, v11
	v_exp_f32_e32 v12, v12
	v_cvt_f32_i32_e32 v6, v6
	v_cvt_f32_i32_e32 v7, v7
	v_mul_f32_e32 v10, v36, v10
	v_mul_f32_e32 v6, v6, v10
	v_mul_f32_e32 v10, v37, v11
	v_fma_f32 v11, v12, s32, s32
	v_rcp_f32_e32 v11, v11
	v_mul_f32_e32 v12, 0xb7afc6c0, v35
	v_exp_f32_e32 v12, v12
	v_mul_f32_e32 v7, v7, v10
	v_mul_f32_e32 v10, v34, v11
	v_mul_f32_e32 v11, 0xb7afc6c0, v32
	v_mul_f32_e32 v4, v4, v10
	v_fma_f32 v10, v12, s32, s32
	v_exp_f32_e32 v11, v11
	v_mul_f32_e32 v12, 0xb7afc6c0, v33
	v_exp_f32_e32 v12, v12
	v_rcp_f32_e32 v10, v10
	v_fma_f32 v11, v11, s32, s32
	v_rcp_f32_e32 v11, v11
	v_fma_f32 v12, v12, s32, s32
	v_rcp_f32_e32 v12, v12
	v_mul_f32_e32 v10, v35, v10
	v_cvt_f32_i32_e32 v2, v2
	v_cvt_f32_i32_e32 v3, v3
	v_mul_f32_e32 v5, v5, v10
	v_mul_f32_e32 v10, v32, v11
	v_mul_f32_e32 v10, v2, v10
	v_mul_f32_e32 v2, v33, v12
	v_mul_f32_e32 v11, v3, v2
	v_med3_f32 v3, v8, s63, v154
	v_med3_f32 v8, v9, s63, v154
	v_cvt_pk_fp8_f32 v2, v3, v8
	v_med3_f32 v4, v4, s63, v154
	v_med3_f32 v5, v5, s63, v154
	v_cvt_pk_fp8_f32 v3, v4, v5
	v_med3_f32 v6, v6, s63, v154
	v_med3_f32 v7, v7, s63, v154
	v_med3_f32 v4, v10, s63, v154
	v_med3_f32 v5, v11, s63, v154
	v_cvt_pk_fp8_f32 v2, v6, v7 op_sel:[0,0,1]
	v_cvt_pk_fp8_f32 v3, v4, v5 op_sel:[0,0,1]
	v_add_u32_e32 v12, 0xb0, v156
	v_mad_i64_i32 v[4:5], s[4:5], v12, s64, v[14:15]
	v_lshl_add_u64 v[0:1], v[4:5], 0, v[0:1]
	s_and_b64 vcc, exec, s[2:3]
	s_mov_b64 s[2:3], -1
	global_store_dwordx2 v[0:1], v[2:3], off
	s_cbranch_vccnz .LBB0_4732
	s_andn2_b64 vcc, exec, s[14:15]
	s_cbranch_vccnz .LBB0_4731
	s_barrier
	s_branch .LBB0_4731
